# one static s_setprio 1 for waves 4-7 over the attention phase (reset at its end), on top of the GEMM accumulator-pair order
# baseline (speedup 1.0000x reference)
.LBB0_389:
	v_writelane_b32 v254, s91, 21
	v_writelane_b32 v254, s92, 22
	s_nop 1
	v_writelane_b32 v254, s93, 23
	v_writelane_b32 v254, s90, 24
	v_writelane_b32 v254, s88, 25
	s_nop 1
	v_writelane_b32 v254, s89, 26
	s_or_b64 exec, exec, s[0:1]
	s_waitcnt lgkmcnt(0)
	v_mov_b32_e32 v0, v215
	s_barrier
	v_readfirstlane_b32 s100, v215
	s_cmp_lt_u32 s100, 0x100
	s_cbranch_scc1 .Lattn_prio_skip
	s_setprio 1
.Lattn_prio_skip:
	v_and_b32_e32 v4, 64, v34
	v_and_b32_e32 v0, 63, v0
	v_lshlrev_b32_e32 v0, 2, v0
	v_lshrrev_b32_e32 v5, 6, v215
	v_lshlrev_b32_e32 v5, 10, v5
	v_add_u32_e32 v5, 0x20000, v5
	v_add_u32_e32 v5, v5, v0
	ds_read_b32 v1, v5
	ds_read_b32 v2, v5 offset:256
	ds_read_b32 v3, v5 offset:512
	ds_read_b32 v0, v5 offset:768
	v_xor_b32_e32 v5, 1, v34
	v_add_u32_e32 v4, 64, v4
	v_cmp_lt_i32_e32 vcc, v5, v4
	v_xor_b32_e32 v6, 2, v34
	v_xor_b32_e32 v7, 4, v34
	v_cndmask_b32_e32 v5, v34, v5, vcc
	v_lshlrev_b32_e32 v212, 2, v5
	v_cmp_lt_i32_e32 vcc, v6, v4
	v_xor_b32_e32 v8, 8, v34
	v_xor_b32_e32 v9, 16, v34
	v_cndmask_b32_e32 v6, v34, v6, vcc
	v_lshlrev_b32_e32 v213, 2, v6
	v_cmp_lt_i32_e32 vcc, v7, v4
	v_xor_b32_e32 v10, 32, v34
	s_add_u32 s92, s62, 0x5c00000
	s_addc_u32 s93, s63, 0
	s_cmpk_gt_i32 s33, 0xff
	s_mov_b32 s7, 0
	s_waitcnt lgkmcnt(2)
	v_mul_f32_e32 v5, v1, v2
	ds_bpermute_b32 v5, v212, v5
	s_waitcnt lgkmcnt(1)
	v_mul_f32_e32 v11, v3, v0
	ds_bpermute_b32 v11, v212, v11
	s_waitcnt lgkmcnt(1)
	v_fmac_f32_e32 v5, v1, v2
	v_cndmask_b32_e32 v2, v34, v7, vcc
	s_waitcnt lgkmcnt(0)
	v_fmac_f32_e32 v11, v3, v0
	ds_bpermute_b32 v0, v213, v5
	ds_bpermute_b32 v1, v213, v11
	v_lshlrev_b32_e32 v214, 2, v2
	v_cmp_lt_i32_e32 vcc, v8, v4
	s_waitcnt lgkmcnt(1)
	v_add_f32_e32 v0, v5, v0
	s_waitcnt lgkmcnt(0)
	v_add_f32_e32 v1, v11, v1
	ds_bpermute_b32 v2, v214, v0
	ds_bpermute_b32 v3, v214, v1
	v_cndmask_b32_e32 v5, v34, v8, vcc
	v_lshlrev_b32_e32 v216, 2, v5
	v_cmp_lt_i32_e32 vcc, v9, v4
	s_waitcnt lgkmcnt(1)
	v_add_f32_e32 v0, v0, v2
	s_waitcnt lgkmcnt(0)
	v_add_f32_e32 v1, v1, v3
	ds_bpermute_b32 v2, v216, v0
	ds_bpermute_b32 v3, v216, v1
	v_cndmask_b32_e32 v5, v34, v9, vcc
	v_lshlrev_b32_e32 v219, 2, v5
	v_cmp_lt_i32_e32 vcc, v10, v4
	s_waitcnt lgkmcnt(1)
	v_add_f32_e32 v0, v0, v2
	s_waitcnt lgkmcnt(0)
	v_add_f32_e32 v1, v1, v3
	ds_bpermute_b32 v2, v219, v0
	ds_bpermute_b32 v3, v219, v1
	v_cndmask_b32_e32 v4, v34, v10, vcc
	v_lshlrev_b32_e32 v223, 2, v4
	s_waitcnt lgkmcnt(1)
	v_add_f32_e32 v0, v0, v2
	s_waitcnt lgkmcnt(0)
	v_add_f32_e32 v1, v1, v3
	ds_bpermute_b32 v2, v223, v0
	ds_bpermute_b32 v3, v223, v1
	s_cbranch_scc1 .LBB0_483
	s_waitcnt lgkmcnt(1)
	v_add_f32_e32 v0, v0, v2
	s_waitcnt lgkmcnt(0)
	v_add_f32_e32 v1, v1, v3
	v_mul_f32_e32 v0, 0x3fb8aa3b, v0
	v_mul_f32_e32 v1, 0x3fb8aa3b, v1
	v_exp_f32_e32 v0, v0
	v_exp_f32_e32 v1, v1
	s_add_u32 s0, s62, 0xde00000
	v_writelane_b32 v254, s0, 27
	s_addc_u32 s0, s63, 0
	v_writelane_b32 v254, s0, 28
	v_sub_f32_e32 v0, v0, v1
	v_add_f32_e32 v217, 0x3e4ccccd, v0
	v_mov_b32_e32 v205, 0
	s_mov_b64 s[8:9], 0x80
	s_mov_b64 s[12:13], 0x10000
	s_mov_b64 s[16:17], 0x20000
	s_mov_b64 s[18:19], 0x30000
	s_mov_b64 s[70:71], 0x10080
	s_mov_b64 s[72:73], 0x40000
	s_mov_b64 s[74:75], 0x11f20000
	s_mov_b64 s[76:77], 0x11f20080
	s_mov_b64 s[78:79], 0x50000
	s_mov_b64 s[80:81], 0x11f30000
	s_mov_b64 s[82:83], 0x11f30080
	s_mov_b64 s[84:85], 0x11f10000
	s_mov_b64 s[86:87], 0x11f10080
	v_mov_b32_e32 v218, 0x358637bd
	v_mov_b32_e32 v220, 0xff800000
	v_writelane_b32 v254, s92, 29
	v_writelane_b32 v254, s93, 30
	s_branch .LBB0_392

.LBB0_483:
	s_setprio 0
	v_mov_b32_e32 v0, v215
	v_mov_b32_e32 v1, 0
	v_readfirstlane_b32 s3, v0
	v_and_b32_e32 v80, 63, v0
	s_and_b32 s0, s3, 0xc0
	v_or_b32_e32 v81, s0, v80
	v_lshlrev_b32_e32 v0, 3, v81
	s_waitcnt lgkmcnt(0)
	v_lshl_add_u64 v[2:3], s[22:23], 0, v[0:1]
	s_movk_i32 s0, 0x1000
	v_add_co_u32_e32 v4, vcc, s0, v2
	s_movk_i32 s0, 0x2000
	s_nop 0
	v_addc_co_u32_e32 v5, vcc, 0, v3, vcc
	v_add_co_u32_e32 v6, vcc, s0, v2
	s_movk_i32 s0, 0x3000
	s_nop 0
	v_addc_co_u32_e32 v7, vcc, 0, v3, vcc
	v_add_co_u32_e32 v8, vcc, s0, v2
	s_movk_i32 s0, 0x4000
	s_nop 0
	v_addc_co_u32_e32 v9, vcc, 0, v3, vcc
	v_add_co_u32_e32 v10, vcc, s0, v2
	s_movk_i32 s0, 0x5000
	s_nop 0
	v_addc_co_u32_e32 v11, vcc, 0, v3, vcc
	v_add_co_u32_e32 v12, vcc, s0, v2
	s_movk_i32 s0, 0x6000
	s_nop 0
	v_addc_co_u32_e32 v13, vcc, 0, v3, vcc
	v_add_co_u32_e32 v14, vcc, s0, v2
	s_movk_i32 s0, 0x7000
	s_nop 0
	v_addc_co_u32_e32 v15, vcc, 0, v3, vcc
	global_load_dwordx2 v[16:17], v[6:7], off
	global_load_dwordx2 v[18:19], v[6:7], off offset:2048
	global_load_dwordx2 v[20:21], v[10:11], off offset:-4096
	global_load_dwordx2 v[22:23], v[10:11], off
	global_load_dwordx2 v[24:25], v[10:11], off offset:2048
	global_load_dwordx2 v[26:27], v[14:15], off offset:-4096
	global_load_dwordx2 v[28:29], v[14:15], off
	global_load_dwordx2 v[30:31], v[14:15], off offset:2048
	v_add_co_u32_e32 v10, vcc, s0, v2
	s_mov_b32 s0, 0x8000
	s_nop 0
	v_addc_co_u32_e32 v11, vcc, 0, v3, vcc
	v_add_co_u32_e32 v14, vcc, s0, v2
	s_mov_b32 s0, 0x9000
	s_nop 0
	v_addc_co_u32_e32 v15, vcc, 0, v3, vcc
	global_load_dwordx2 v[32:33], v[4:5], off offset:2048
	global_load_dwordx2 v[34:35], v[8:9], off offset:2048
	global_load_dwordx2 v[36:37], v[12:13], off offset:2048
	global_load_dwordx2 v[38:39], v[10:11], off offset:2048
	v_add_co_u32_e32 v4, vcc, s0, v2
	s_mov_b32 s0, 0xa000
	s_nop 0
	v_addc_co_u32_e32 v5, vcc, 0, v3, vcc
	v_add_co_u32_e32 v8, vcc, s0, v2
	s_mov_b32 s0, 0xb000
	s_nop 0
	v_addc_co_u32_e32 v9, vcc, 0, v3, vcc
	v_add_co_u32_e32 v10, vcc, s0, v2
	s_mov_b32 s0, 0xc000
	s_nop 0
	v_addc_co_u32_e32 v11, vcc, 0, v3, vcc
	v_add_co_u32_e32 v12, vcc, s0, v2
	s_mov_b32 s0, 0xd000
	s_nop 0
	v_addc_co_u32_e32 v13, vcc, 0, v3, vcc
	global_load_dwordx2 v[40:41], v[14:15], off offset:-4096
	global_load_dwordx2 v[42:43], v[14:15], off
	global_load_dwordx2 v[44:45], v[14:15], off offset:2048
	global_load_dwordx2 v[46:47], v[8:9], off offset:-4096
	global_load_dwordx2 v[48:49], v[8:9], off
	global_load_dwordx2 v[50:51], v[8:9], off offset:2048
	global_load_dwordx2 v[52:53], v[12:13], off offset:-4096
	global_load_dwordx2 v[54:55], v[12:13], off
	v_add_co_u32_e32 v8, vcc, s0, v2
	s_mov_b32 s0, 0xe000
	s_nop 0
	v_addc_co_u32_e32 v9, vcc, 0, v3, vcc
	v_add_co_u32_e32 v14, vcc, s0, v2
	v_lshlrev_b32_e32 v82, 5, v80
	s_nop 0
	v_addc_co_u32_e32 v15, vcc, 0, v3, vcc
	v_add_co_u32_e32 v2, vcc, 0xf000, v2
	global_load_dwordx2 v[56:57], v[12:13], off offset:2048
	global_load_dwordx2 v[58:59], v[14:15], off offset:-4096
	global_load_dwordx2 v[60:61], v[14:15], off
	global_load_dwordx2 v[62:63], v[14:15], off offset:2048
	v_addc_co_u32_e32 v3, vcc, 0, v3, vcc
	global_load_dwordx2 v[64:65], v[4:5], off offset:2048
	global_load_dwordx2 v[66:67], v[10:11], off offset:2048
	global_load_dwordx2 v[68:69], v[8:9], off offset:2048
	global_load_dwordx2 v[70:71], v[2:3], off
	global_load_dwordx2 v[72:73], v0, s[22:23]
	global_load_dwordx2 v[74:75], v0, s[22:23] offset:2048
	global_load_dwordx2 v[76:77], v[6:7], off offset:-4096
	global_load_dwordx2 v[78:79], v0, s[24:25]
	s_nop 0
	global_load_dwordx4 v[0:3], v82, s[26:27] offset:16
	global_load_dwordx4 v[4:7], v82, s[28:29] offset:16
	global_load_dwordx4 v[8:11], v82, s[26:27]
	global_load_dwordx4 v[12:15], v82, s[28:29]
	s_ashr_i32 s10, s3, 6
	v_lshlrev_b32_e32 v84, 3, v80
	v_or_b32_e32 v80, s10, v80
	v_lshlrev_b32_e32 v101, 1, v81
	v_cmp_eq_u32_e64 s[4:5], 0, v80
	s_and_saveexec_b64 s[0:1], s[4:5]
	v_readlane_b32 s68, v254, 0
	v_readlane_b32 s76, v254, 19
	v_readlane_b32 s69, v254, 1
	v_readlane_b32 s70, v254, 2
	v_readlane_b32 s71, v254, 3
	v_readlane_b32 s72, v254, 4
	v_readlane_b32 s73, v254, 5
	v_readlane_b32 s74, v254, 6
	v_readlane_b32 s75, v254, 7
	v_readlane_b32 s77, v254, 20
	s_cbranch_execz .LBB0_489
	s_mov_b64 s[8:9], exec
	v_mbcnt_lo_u32_b32 v80, s8, 0
	v_mbcnt_hi_u32_b32 v80, s9, v80
	v_cmp_eq_u32_e32 vcc, 0, v80
	s_and_saveexec_b64 s[6:7], vcc
	s_cbranch_execz .LBB0_486
	v_mov_b32_e32 v81, 0
	v_mov_b32_e32 v82, 2
	global_atomic_add v81, v81, v82, s[62:63] offset:128 sc0
